# P10 walks each XCD's row tiles newest-first (ACT still in the infinity cache); P1+P8 unit order 4x8; attention max tree; batched skinny loads
# baseline (speedup 1.0000x reference)
; #define INP(k) ((const float*)(GAS const float*)KARG64(8 * (k)))
;     __device__ __forceinline__ bool next(int i, pg8::Unit& u) const { const int L = i * G + c; if (L >= NG * 8) return false; u.pm = (L >> 3) * 9 + (L & 7); u.pn = L >> 3; return true; }
;     __host__ __device__ bool next(int i, Unit& u) const {
;     ...
;         int wgid = (int)L; { const int q = nwg / NXCD, r = nwg % NXCD, xcd = wgid % NXCD, off = wgid / NXCD; wgid = (xcd < r ? xcd * (q + 1) : r * (q + 1) + (xcd - r) * q) + off; }
;         const int nig = WGM * nN, gid = wgid / nig, fm = gid * WGM, gsz = (nM - fm) < WGM ? (nM - fm) : WGM;
;         u.pm = fm + ((wgid % nig) % gsz); u.pn = (wgid % nig) / gsz; return true;
; __global__ void __launch_bounds__(NWAVES * 64, 2) hybrid_fwd(Params P) {
;     ...
;             const float* cw = INP(26); pg8::Unit uu; int lastpm = -1;
;             for (int ui = 0; S.next(ui, uu); ++ui) {
;                 const int pm = uu.pm; if (pm == lastpm) continue; lastpm = pm;
.LBB0_1300:
	s_ashr_i32 s10, s13, 3
	s_add_i32 s10, s15, s10
	s_ashr_i32 s11, s10, 31
	s_lshr_b32 s11, s11, 29
	s_add_i32 s11, s10, s11
	s_ashr_i32 s13, s11, 3
	s_lshl_b32 s13, s13, 1
	s_sub_i32 s14, 0x80, s13
	s_min_i32 s14, s14, 2
	s_abs_i32 s14, s14
	v_cvt_f32_u32_e32 v4, s14
	s_sub_i32 s15, 0, s14
	s_and_b32 s11, s11, -8
	s_sub_i32 s10, s10, s11
	v_rcp_iflag_f32_e32 v4, v4
	s_ashr_i32 s11, s10, 31
	s_abs_i32 s10, s10
	v_mul_f32_e32 v4, 0x4f7ffffe, v4
	v_cvt_u32_f32_e32 v4, v4
	s_nop 0
	v_readfirstlane_b32 s25, v4
	s_mul_i32 s15, s15, s25
	s_mul_hi_u32 s15, s25, s15
	s_add_i32 s25, s25, s15
	s_mul_hi_u32 s15, s10, s25
	s_mul_i32 s15, s15, s14
	s_sub_i32 s10, s10, s15
	s_sub_i32 s15, s10, s14
	s_cmp_ge_u32 s10, s14
	s_cselect_b32 s10, s15, s10
	s_sub_i32 s15, s10, s14
	s_cmp_ge_u32 s10, s14
	s_cselect_b32 s10, s15, s10
	s_xor_b32 s10, s10, s11
	s_sub_i32 s10, s10, s11
	s_add_i32 s25, s13, s10
	s_xor_b32 s25, s25, 15
	v_cmp_lt_i64_e32 vcc, s[4:5], v[0:1]
	s_mov_b64 s[4:5], -1
	s_cbranch_vccz .LBB0_1293

; #define PG8_BAR __builtin_amdgcn_s_barrier()
; template <class Epi, class Sched, bool ALIGN_EPI = false, bool SP2 = false>
; __device__ __forceinline__ void gemm_phase(PG8_LAS unsigned char* lds, const Gemm g, const Sched& S, const Epi& E) {
;     ...
;     const int tid = tid_, wid = __builtin_amdgcn_readfirstlane(tid >> 6), lane = tid & 63, wr = wid >> 2, wc = wid & 3, fr = lane & 15, fq = lane >> 4;
;     const int K = g.K, nt = K / BK;
;     unsigned voffA[2], voffB[2];
; #pragma unroll
;     for (int i = 0; i < 2; ++i) { int R, C; stage_rc(tid * 16 + i * 8192, R, C); const int Rb = Epi::PERM ? ((R & ~31) + perm32(R & 31)) : R;
;         const int Ra = Epi::ROWPERM ? ((R & 64) + 4 * (R & 15) + ((R >> 4) & 3)) : R;
;         voffA[i] = (unsigned)(Ra * g.lda + C) * 2u; voffB[i] = (unsigned)(Rb * g.ldb + C) * 2u; }
;     const size_t kstep = (size_t)(BK * 2);
;     const size_t hstepA = (size_t)HALF * g.lda * 2, hstepB = (size_t)HALF * g.ldb * 2;
;     const size_t tstepA = 2 * hstepA, tstepB = 2 * hstepB;
;     const unsigned ldsw = (unsigned)wid * 1024u;
;     const int aoff = lds_byte(wr * 64 + fr, fq * 8), boff = lds_byte(wc * 32 + fr, fq * 8);
;     ...
;     if (!S.next(0, cur)) return;
;     f32x4 acc[2][2][4][2];
; #pragma unroll
;     for (int a = 0; a < 2; ++a)
; #pragma unroll
;         for (int b = 0; b < 2; ++b)
; #pragma unroll
;             for (int m = 0; m < 4; ++m)
; #pragma unroll
;                 for (int n = 0; n < 2; ++n) acc[a][b][m][n] = (f32x4){0.f, 0.f, 0.f, 0.f};
;     bf16x8 At[4][2], B0[2][2], B1[2][2];
;     const char* cA = (const char*)g.A + (size_t)cur.pm * tstepA; const char* cB = (const char*)g.Bt + (size_t)cur.pn * tstepB;
;     S.a_ready(cur);
;     if constexpr (SP2) {
;         PG8_STAGE(PG8_SB(0, 0), cB, voffB); PG8_STAGE(PG8_SB(0, 1), cB + hstepB, voffB); PG8_STAGE(PG8_SA(0, 0), cA, voffA); PG8_STAGE(PG8_SA(0, 1), cA + hstepA, voffA);
;         if (wr == 1) PG8_BAR;
;         PG8_WAIT_V(2); PG8_BAR;
;         PG8_STAGE(PG8_SB(1, 0), cB + kstep, voffB); PG8_STAGE(PG8_SA(1, 0), cA + kstep, voffA); PG8_STAGE(PG8_SB(1, 1), cB + hstepB + kstep, voffB);
;         PG8_WAIT_V(6); PG8_BAR;
;     } else {
;         PG8_STAGE(PG8_SB(0, 0), cB, voffB); PG8_STAGE(PG8_SA(0, 0), cA, voffA); PG8_STAGE(PG8_SB(0, 1), cB + hstepB, voffB); PG8_STAGE(PG8_SA(0, 1), cA + hstepA, voffA);
;         if (wr == 1) PG8_BAR;
;         PG8_WAIT_V(4); PG8_BAR;
.LBB0_1313:
	v_ashrrev_i32_e32 v1, 31, v218
	v_lshrrev_b32_e32 v1, 26, v1
	v_add_u32_e32 v1, v218, v1
	v_ashrrev_i32_e32 v8, 6, v1
	v_bfe_i32 v1, v218, 27, 1
	v_lshlrev_b32_e32 v0, 4, v218
	v_lshrrev_b32_e32 v1, 22, v1
	v_add_u32_e32 v1, v0, v1
	v_and_b32_e32 v1, 0xfffffc00, v1
	v_sub_u32_e32 v1, v0, v1
	v_lshrrev_b32_e32 v2, 4, v1
	v_bitop3_b32 v1, v2, v1, 32 bitop3:0x6c
	v_ashrrev_i32_e32 v3, 31, v1
	v_lshrrev_b32_e32 v3, 26, v3
	v_lshlrev_b32_e32 v2, 3, v8
	v_add_u32_e32 v3, v1, v3
	v_and_b32_e32 v2, -16, v2
	v_ashrrev_i32_e32 v10, 6, v3
	v_and_b32_e32 v3, 0xc0, v3
	v_add_u32_e32 v2, v10, v2
	v_lshlrev_b32_e32 v4, 5, v8
	v_sub_u32_e32 v1, v1, v3
	v_mov_b32_e32 v3, 1
	v_and_b32_e32 v9, 32, v4
	v_ashrrev_i16_sdwa v1, v3, sext(v1) dst_sel:DWORD dst_unused:UNUSED_PAD src0_sel:DWORD src1_sel:BYTE_0
	v_lshlrev_b32_e32 v4, 1, v2
	v_lshrrev_b32_e32 v5, 2, v2
	v_and_b32_e32 v6, 3, v10
	s_mov_b32 s7, 0xffffe0
	v_bfe_i32 v11, v1, 0, 16
	v_and_b32_e32 v4, 24, v4
	v_and_b32_e32 v5, 4, v5
	v_and_or_b32 v6, v2, s7, v6
	s_movk_i32 s16, 0xb00
	v_add_u32_e32 v1, v9, v11
	v_or3_b32 v4, v6, v5, v4
	v_mul_lo_u32 v2, v2, s16
	v_add_lshl_u32 v128, v1, v2, 1
	v_mul_u32_u24_e32 v2, 0xb00, v4
	v_add_u32_e32 v0, 0x2000, v0
	v_add_lshl_u32 v130, v2, v1, 1
	v_ashrrev_i32_e32 v1, 31, v0
	v_lshrrev_b32_e32 v1, 22, v1
	v_add_u32_e32 v1, v0, v1
	v_ashrrev_i32_e32 v12, 10, v1
	v_mul_i32_i24_e32 v1, 0x400, v12
	v_sub_u32_e32 v0, v0, v1
	v_lshrrev_b32_e32 v1, 4, v0
	v_bitop3_b32 v0, v1, v0, 32 bitop3:0x6c
	v_ashrrev_i32_e32 v2, 31, v0
	s_waitcnt lgkmcnt(0)
	s_add_u32 s28, s10, 0xca00000
	v_lshrrev_b32_e32 v2, 26, v2
	s_addc_u32 s29, s11, 0
	v_lshlrev_b32_e32 v1, 3, v12
	v_add_u32_e32 v2, v0, v2
	s_add_u32 s30, s8, 0x1880000
	v_and_b32_e32 v1, -16, v1
	v_ashrrev_i32_e32 v13, 6, v2
	v_lshlrev_b32_e32 v4, 5, v12
	s_addc_u32 s31, s9, 0
	v_add_u32_e32 v1, v13, v1
	v_and_b32_e32 v14, 32, v4
	v_and_b32_e32 v4, 3, v13
	s_add_i32 s6, s17, s6
	v_and_or_b32 v4, v1, s7, v4
	s_ashr_i32 s7, s6, 31
	s_lshr_b32 s7, s7, 29
	s_add_i32 s7, s6, s7
	s_ashr_i32 s8, s7, 3
	s_and_b32 s7, s7, 0xfff8
	s_sub_i32 s6, s6, s7
	s_bfe_u32 s7, s6, 0x10007
	s_add_i32 s7, s6, s7
	s_bfe_i32 s9, s7, 0x80000
	s_and_b32 s7, s7, 0xfe
	s_sub_i32 s6, s6, s7
	s_lshl_b32 s8, s8, 1
	s_sext_i32_i16 s9, s9
	s_sext_i32_i8 s6, s6
	s_ashr_i32 s12, s14, 6
	v_and_b32_e32 v2, 0xc0, v2
	s_add_i32 s45, s8, s6
	s_xor_b32 s45, s45, 15
	s_ashr_i32 s6, s9, 1
	v_sub_u32_e32 v0, v0, v2
	s_ashr_i32 s15, s14, 8
	s_lshl_b32 s33, s12, 10
	s_lshr_b32 s17, s9, 1
	s_mul_hi_i32 s7, s6, 0x160000
	s_mul_i32 s6, s6, 0x160000
	v_ashrrev_i16_sdwa v0, v3, sext(v0) dst_sel:DWORD dst_unused:UNUSED_PAD src0_sel:DWORD src1_sel:BYTE_0
	v_lshlrev_b32_e32 v2, 1, v1
	v_lshrrev_b32_e32 v3, 2, v1
	s_add_u32 s20, s30, s6
	v_bfe_i32 v15, v0, 0, 16
	v_and_b32_e32 v2, 24, v2
	v_and_b32_e32 v3, 4, v3
	s_addc_u32 s21, s31, s7
	s_add_i32 s34, s33, 0
	v_add_u32_e32 v0, v14, v15
	v_or3_b32 v2, v4, v3, v2
	v_mul_lo_u32 v1, v1, s16
	s_add_i32 m0, s34, 0x10000
	v_add_lshl_u32 v132, v0, v1, 1
	v_mul_u32_u24_e32 v1, 0xb00, v2
	global_load_lds_dwordx4 v130, s[20:21]
	s_add_i32 m0, s34, 0x12000
	v_add_lshl_u32 v134, v1, v0, 1
	s_add_u32 s6, s20, 0xb0000
	global_load_lds_dwordx4 v134, s[20:21]
	s_addc_u32 s7, s21, 0
	s_add_i32 m0, s34, 0x14000
	s_mul_i32 s10, s45, 0x160000
	global_load_lds_dwordx4 v130, s[6:7]
	s_add_i32 m0, s34, 0x16000
	s_mul_hi_i32 s8, s45, 0x160000
	s_add_u32 s18, s28, s10
	s_addc_u32 s19, s29, s8
	s_add_i32 s35, s34, 0x2000
	global_load_lds_dwordx4 v134, s[6:7]
	s_mov_b32 m0, s34
	s_add_u32 s6, s18, 0xb0000
	global_load_lds_dwordx4 v128, s[18:19]
	s_mov_b32 m0, s35
	s_addc_u32 s7, s19, 0
	s_add_i32 s36, s34, 0x4000
	global_load_lds_dwordx4 v132, s[18:19]
	s_mov_b32 m0, s36
	s_add_i32 s37, s34, 0x6000
	global_load_lds_dwordx4 v128, s[6:7]
	s_mov_b32 m0, s37
	v_mov_b32_e32 v131, 0
	global_load_lds_dwordx4 v132, s[6:7]
	s_load_dwordx2 s[6:7], s[4:5], 0xe8
	v_mov_b32_e32 v135, v131
	v_mov_b32_e32 v129, v131
	v_mov_b32_e32 v133, v131
	s_cmp_eq_u32 s15, 1
	s_mov_b32 s38, 0
	v_lshl_add_u64 v[6:7], s[20:21], 0, v[130:131]
	v_lshl_add_u64 v[4:5], s[20:21], 0, v[134:135]
	v_lshl_add_u64 v[0:1], s[18:19], 0, v[128:129]
	s_cselect_b64 s[8:9], -1, 0
	s_cmp_lg_u32 s15, 1
	v_lshl_add_u64 v[2:3], s[18:19], 0, v[132:133]
	s_cbranch_scc1 .LBB0_1315
	s_barrier

;     __device__ __forceinline__ bool next(int i, pg8::Unit& u) const { const int L = i * G + c; if (L >= NG * 8) return false; u.pm = (L >> 3) * 9 + (L & 7); u.pn = L >> 3; return true; }
;     __host__ __device__ bool next(int i, Unit& u) const {
;     ...
;         int wgid = (int)L; { const int q = nwg / NXCD, r = nwg % NXCD, xcd = wgid % NXCD, off = wgid / NXCD; wgid = (xcd < r ? xcd * (q + 1) : r * (q + 1) + (xcd - r) * q) + off; }
;         const int nig = WGM * nN, gid = wgid / nig, fm = gid * WGM, gsz = (nM - fm) < WGM ? (nM - fm) : WGM;
;         u.pm = fm + ((wgid % nig) % gsz); u.pn = (wgid % nig) / gsz; return true;
; template <class Epi, class Sched, bool ALIGN_EPI = false, bool SP2 = false>
; __device__ __forceinline__ void gemm_phase(PG8_LAS unsigned char* lds, const Gemm g, const Sched& S, const Epi& E) {
;     ...
;         const bool has_next = S.next(ui + 1, nxt);
;         const char* nA = has_next ? (const char*)g.A + (size_t)nxt.pm * tstepA : cA; const char* nB = has_next ? (const char*)g.Bt + (size_t)nxt.pn * tstepB : cB;
.LBB0_1323:
	s_ashr_i32 s0, s16, 3
	s_add_i32 s0, s22, s0
	s_ashr_i32 s1, s0, 31
	s_lshr_b32 s1, s1, 29
	s_add_i32 s1, s0, s1
	s_ashr_i32 s16, s1, 3
	s_lshl_b32 s16, s16, 1
	s_sub_i32 s17, 0x80, s16
	s_min_i32 s17, s17, 2
	s_abs_i32 s22, s17
	v_cvt_f32_u32_e32 v0, s22
	s_sub_i32 s24, 0, s22
	s_and_b32 s1, s1, -8
	s_sub_i32 s0, s0, s1
	v_rcp_iflag_f32_e32 v0, v0
	s_abs_i32 s1, s0
	s_xor_b32 s23, s0, s17
	s_ashr_i32 s23, s23, 31
	v_mul_f32_e32 v0, 0x4f7ffffe, v0
	v_cvt_u32_f32_e32 v0, v0
	s_nop 0
	v_readfirstlane_b32 s25, v0
	s_mul_i32 s24, s24, s25
	s_mul_hi_u32 s24, s25, s24
	s_add_i32 s25, s25, s24
	s_mul_hi_u32 s24, s1, s25
	s_mul_i32 s25, s24, s22
	s_sub_i32 s1, s1, s25
	s_add_i32 s43, s24, 1
	s_sub_i32 s25, s1, s22
	s_cmp_ge_u32 s1, s22
	s_cselect_b32 s24, s43, s24
	s_cselect_b32 s1, s25, s1
	s_add_i32 s25, s24, 1
	s_cmp_ge_u32 s1, s22
	s_cselect_b32 s1, s25, s24
	s_xor_b32 s1, s1, s23
	s_sub_i32 s43, s1, s23
	s_mul_i32 s1, s43, s17
	s_sub_i32 s0, s0, s1
	s_add_i32 s44, s16, s0
	s_xor_b32 s44, s44, 15
